# DF diagonal tiles: causal mask as 32 compare/select pairs on 4 SGPR pairs instead of the 96-instruction cumulative form
# speedup vs baseline: 1.0018x; 1.0018x over previous
; __device__ __forceinline__ void mask_incl(f32x16& p0, f32x16& p1, int dq) {
;     const float NEG = -__builtin_inff();
; #pragma unroll
;     for (int r = 0; r < 16; ++r) { const int c = (r & 3) + 8 * (r >> 2);
;         if (dq - c < 0) p0[r] = NEG;
;         if (dq - c - 32 < 0) p1[r] = NEG; }
; }
.Ldf_diag:
	s_waitcnt lgkmcnt(4)
	v_mfma_f32_32x32x16_bf16 v[146:161], v[146:149], v[162:165], 0
	v_mfma_f32_32x32x16_bf16 v[146:161], v[210:213], v[166:169], v[146:161]
	v_mfma_f32_32x32x16_bf16 v[146:161], v[226:229], v[170:173], v[146:161]
	v_mfma_f32_32x32x16_bf16 v[146:161], v[246:249], v[174:177], v[146:161]
	s_waitcnt lgkmcnt(3)
	v_mfma_f32_32x32x16_bf16 v[146:161], v[218:221], v[178:181], v[146:161]
	s_waitcnt lgkmcnt(2)
	v_mfma_f32_32x32x16_bf16 v[146:161], v[234:237], v[182:185], v[146:161]
	s_waitcnt lgkmcnt(1)
	v_mfma_f32_32x32x16_bf16 v[146:161], v[238:241], v[186:189], v[146:161]
	s_waitcnt lgkmcnt(0)
	v_mfma_f32_32x32x16_bf16 v[146:161], v[242:245], v[190:193], v[146:161]
	v_cmp_gt_i32_e64 s[60:61], 0, v215
	v_cmp_gt_i32_e64 s[62:63], 1, v215
	v_cmp_gt_i32_e64 s[64:65], 2, v215
	v_cmp_gt_i32_e64 s[66:67], 3, v215
	v_cndmask_b32_e64 v130, v130, v225, s[60:61]
	v_cndmask_b32_e64 v131, v131, v225, s[62:63]
	v_cndmask_b32_e64 v132, v132, v225, s[64:65]
	v_cndmask_b32_e64 v133, v133, v225, s[66:67]
	v_cmp_gt_i32_e64 s[60:61], 8, v215
	v_cmp_gt_i32_e64 s[62:63], 9, v215
	v_cmp_gt_i32_e64 s[64:65], 10, v215
	v_cmp_gt_i32_e64 s[66:67], 11, v215
	v_cndmask_b32_e64 v134, v134, v225, s[60:61]
	v_cndmask_b32_e64 v135, v135, v225, s[62:63]
	v_cndmask_b32_e64 v136, v136, v225, s[64:65]
	v_cndmask_b32_e64 v137, v137, v225, s[66:67]
	v_cmp_gt_i32_e64 s[60:61], 16, v215
	v_cmp_gt_i32_e64 s[62:63], 17, v215
	v_cmp_gt_i32_e64 s[64:65], 18, v215
	v_cmp_gt_i32_e64 s[66:67], 19, v215
	v_cndmask_b32_e64 v138, v138, v225, s[60:61]
	v_cndmask_b32_e64 v139, v139, v225, s[62:63]
	v_cndmask_b32_e64 v140, v140, v225, s[64:65]
	v_cndmask_b32_e64 v141, v141, v225, s[66:67]
	v_cmp_gt_i32_e64 s[60:61], 24, v215
	v_cmp_gt_i32_e64 s[62:63], 25, v215
	v_cmp_gt_i32_e64 s[64:65], 26, v215
	v_cmp_gt_i32_e64 s[66:67], 27, v215
	v_cndmask_b32_e64 v142, v142, v225, s[60:61]
	v_cndmask_b32_e64 v143, v143, v225, s[62:63]
	v_cndmask_b32_e64 v144, v144, v225, s[64:65]
	v_cndmask_b32_e64 v145, v145, v225, s[66:67]
	v_cmp_gt_i32_e64 s[60:61], 32, v215
	v_cmp_gt_i32_e64 s[62:63], 33, v215
	v_cmp_gt_i32_e64 s[64:65], 34, v215
	v_cmp_gt_i32_e64 s[66:67], 35, v215
	v_cndmask_b32_e64 v146, v146, v225, s[60:61]
	v_cndmask_b32_e64 v147, v147, v225, s[62:63]
	v_cndmask_b32_e64 v148, v148, v225, s[64:65]
	v_cndmask_b32_e64 v149, v149, v225, s[66:67]
	v_cmp_gt_i32_e64 s[60:61], 40, v215
	v_cmp_gt_i32_e64 s[62:63], 41, v215
	v_cmp_gt_i32_e64 s[64:65], 42, v215
	v_cmp_gt_i32_e64 s[66:67], 43, v215
	v_cndmask_b32_e64 v150, v150, v225, s[60:61]
	v_cndmask_b32_e64 v151, v151, v225, s[62:63]
	v_cndmask_b32_e64 v152, v152, v225, s[64:65]
	v_cndmask_b32_e64 v153, v153, v225, s[66:67]
	v_cmp_gt_i32_e64 s[60:61], 48, v215
	v_cmp_gt_i32_e64 s[62:63], 49, v215
	v_cmp_gt_i32_e64 s[64:65], 50, v215
	v_cmp_gt_i32_e64 s[66:67], 51, v215
	v_cndmask_b32_e64 v154, v154, v225, s[60:61]
	v_cndmask_b32_e64 v155, v155, v225, s[62:63]
	v_cndmask_b32_e64 v156, v156, v225, s[64:65]
	v_cndmask_b32_e64 v157, v157, v225, s[66:67]
	v_cmp_gt_i32_e64 s[60:61], 56, v215
	v_cmp_gt_i32_e64 s[62:63], 57, v215
	v_cmp_gt_i32_e64 s[64:65], 58, v215
	v_cmp_gt_i32_e64 s[66:67], 59, v215
	v_cndmask_b32_e64 v158, v158, v225, s[60:61]
	v_cndmask_b32_e64 v159, v159, v225, s[62:63]
	v_cndmask_b32_e64 v160, v160, v225, s[64:65]
	v_cndmask_b32_e64 v161, v161, v225, s[66:67]
	s_branch .LBB0_143
